# v24 + XCD barrier with direct release: last XCD leader bumps all per-XCC generation words (one fewer round trip)
# speedup vs baseline: 1.0095x; 1.0095x over previous
; DI void gbar(unsigned* ctr, unsigned& gen, unsigned G) {
;     asm volatile("s_waitcnt vmcnt(0)" ::: "memory");
;     __syncthreads();
;     gen += 1;
;     if (threadIdx.x == 0) {
;         __builtin_amdgcn_fence(__ATOMIC_RELEASE, "agent");
;         asm volatile("s_waitcnt vmcnt(0)" ::: "memory");
;         __hip_atomic_fetch_add(ctr, 1u, __ATOMIC_RELAXED, __HIP_MEMORY_SCOPE_AGENT);
;         while (__hip_atomic_load(ctr, __ATOMIC_RELAXED, __HIP_MEMORY_SCOPE_AGENT) < gen * G) __builtin_amdgcn_s_sleep(32);
;         __builtin_amdgcn_fence(__ATOMIC_ACQUIRE, "agent");
;         asm volatile("s_waitcnt vmcnt(0)" ::: "memory");
;     }
;     __syncthreads();
; }
.LBB0_1197:
	s_or_b64 exec, exec, s[18:19]
	v_cmp_gt_i32_e32 vcc, 2, v1
	v_cmp_lt_i32_e64 s[2:3], 2, v2
	s_and_b64 s[0:1], vcc, s[2:3]
	v_mov_b32_e32 v210, 0
	s_and_saveexec_b64 s[2:3], s[0:1]
	s_cbranch_execz .LBB0_1205
	s_waitcnt vmcnt(0)
	s_waitcnt lgkmcnt(0)
	v_and_b32_e32 v3, 0x3ff, v0
	v_cmp_eq_u32_e32 vcc, 0, v3
	s_waitcnt vmcnt(0)
	s_barrier
	s_and_saveexec_b64 s[4:5], vcc
	s_cbranch_execz .LBB0_1204
	s_getreg_b32 s1, hwreg(HW_REG_XCC_ID, 0, 4)
	s_lshl_b32 s1, s1, 8
	s_add_u32 s12, s42, 0x600000
	s_addc_u32 s13, s43, 0
	s_add_u32 s12, s12, s1
	s_addc_u32 s13, s13, 0
	s_add_u32 s14, s42, 0x601000
	s_addc_u32 s15, s43, 0
	s_lshr_b32 s16, s86, 3
	v_mov_b32_e32 v2, 0
	v_mov_b32_e32 v3, 1
	v_mov_b32_e32 v7, 1
	global_atomic_add v4, v2, v3, s[12:13] sc0
	v_mul_lo_u32 v8, v7, s16
	s_mov_b32 s0, 0
	s_waitcnt vmcnt(0)
	v_add_u32_e32 v4, 1, v4
	v_cmp_eq_u32_e32 vcc, v4, v8
	s_cbranch_vccz .Lxb_nl_0
	buffer_wbl2 sc1
	s_waitcnt vmcnt(0)
	global_atomic_add v4, v2, v3, s[14:15] sc0
	v_lshlrev_b32_e32 v8, 3, v7
	s_waitcnt vmcnt(0)
	v_add_u32_e32 v4, 1, v4
	v_cmp_eq_u32_e32 vcc, v4, v8
	s_cbranch_vccz .Lxb_wt_0
	global_atomic_add v2, v3, s[14:15] offset:-3968
	global_atomic_add v2, v3, s[14:15] offset:-3712
	global_atomic_add v2, v3, s[14:15] offset:-3456
	global_atomic_add v2, v3, s[14:15] offset:-3200
	global_atomic_add v2, v3, s[14:15] offset:-2944
	global_atomic_add v2, v3, s[14:15] offset:-2688
	global_atomic_add v2, v3, s[14:15] offset:-2432
	global_atomic_add v2, v3, s[14:15] offset:-2176
	global_atomic_add v2, v3, s[14:15] offset:-1920
	global_atomic_add v2, v3, s[14:15] offset:-1664
	global_atomic_add v2, v3, s[14:15] offset:-1408
	global_atomic_add v2, v3, s[14:15] offset:-1152
	global_atomic_add v2, v3, s[14:15] offset:-896
	global_atomic_add v2, v3, s[14:15] offset:-640
	global_atomic_add v2, v3, s[14:15] offset:-384
	global_atomic_add v2, v3, s[14:15] offset:-128
	buffer_inv sc1
	s_waitcnt vmcnt(0)
	s_branch .Lxb_dn_0
.Lxb_wt_0:
.Lxb_nl_0:
	s_sleep 1
	global_load_dword v4, v2, s[12:13] offset:128 sc1
	s_add_u32 s0, s0, 1
	s_waitcnt vmcnt(0)
	v_cmp_ge_u32_e32 vcc, v4, v7
	s_cbranch_vccnz .Lxb_na_0
	s_cmp_lt_u32 s0, 0x20000
	s_cbranch_scc1 .Lxb_nl_0

; DI void gbar(unsigned* ctr, unsigned& gen, unsigned G) {
;     asm volatile("s_waitcnt vmcnt(0)" ::: "memory");
;     __syncthreads();
;     gen += 1;
;     if (threadIdx.x == 0) {
;         __builtin_amdgcn_fence(__ATOMIC_RELEASE, "agent");
;         asm volatile("s_waitcnt vmcnt(0)" ::: "memory");
;         __hip_atomic_fetch_add(ctr, 1u, __ATOMIC_RELAXED, __HIP_MEMORY_SCOPE_AGENT);
;         while (__hip_atomic_load(ctr, __ATOMIC_RELAXED, __HIP_MEMORY_SCOPE_AGENT) < gen * G) __builtin_amdgcn_s_sleep(32);
;         __builtin_amdgcn_fence(__ATOMIC_ACQUIRE, "agent");
;         asm volatile("s_waitcnt vmcnt(0)" ::: "memory");
;     }
;     __syncthreads();
; }
.LBB0_1236:
	s_or_b64 exec, exec, s[22:23]
	s_cmp_lt_i32 s90, 3
	s_cselect_b64 s[0:1], -1, 0
	s_cmp_gt_i32 s91, 3
	s_cselect_b64 s[2:3], -1, 0
	s_and_b64 s[0:1], s[0:1], s[2:3]
	s_andn2_b64 vcc, exec, s[0:1]
	s_cbranch_vccnz .LBB0_1245
	s_waitcnt vmcnt(0)
	v_and_b32_e32 v1, 0x3ff, v0
	v_add_u32_e32 v210, 1, v210
	v_cmp_eq_u32_e32 vcc, 0, v1
	v_mov_b32_e32 v1, s90
	s_waitcnt lgkmcnt(0)
	v_mov_b32_e32 v5, s91
	s_waitcnt vmcnt(0)
	s_barrier
	s_and_saveexec_b64 s[2:3], vcc
	s_cbranch_execz .LBB0_1244
	s_getreg_b32 s1, hwreg(HW_REG_XCC_ID, 0, 4)
	s_lshl_b32 s1, s1, 8
	s_add_u32 s12, s42, 0x600000
	s_addc_u32 s13, s43, 0
	s_add_u32 s12, s12, s1
	s_addc_u32 s13, s13, 0
	s_add_u32 s14, s42, 0x601000
	s_addc_u32 s15, s43, 0
	s_lshr_b32 s16, s86, 3
	v_mov_b32_e32 v2, 0
	v_mov_b32_e32 v3, 1
	v_mov_b32_e32 v7, v210
	global_atomic_add v4, v2, v3, s[12:13] sc0
	v_mul_lo_u32 v8, v7, s16
	s_mov_b32 s0, 0
	s_waitcnt vmcnt(0)
	v_add_u32_e32 v4, 1, v4
	v_cmp_eq_u32_e32 vcc, v4, v8
	s_cbranch_vccz .Lxb_nl_1
	buffer_wbl2 sc1
	s_waitcnt vmcnt(0)
	global_atomic_add v4, v2, v3, s[14:15] sc0
	v_lshlrev_b32_e32 v8, 3, v7
	s_waitcnt vmcnt(0)
	v_add_u32_e32 v4, 1, v4
	v_cmp_eq_u32_e32 vcc, v4, v8
	s_cbranch_vccz .Lxb_wt_1
	global_atomic_add v2, v3, s[14:15] offset:-3968
	global_atomic_add v2, v3, s[14:15] offset:-3712
	global_atomic_add v2, v3, s[14:15] offset:-3456
	global_atomic_add v2, v3, s[14:15] offset:-3200
	global_atomic_add v2, v3, s[14:15] offset:-2944
	global_atomic_add v2, v3, s[14:15] offset:-2688
	global_atomic_add v2, v3, s[14:15] offset:-2432
	global_atomic_add v2, v3, s[14:15] offset:-2176
	global_atomic_add v2, v3, s[14:15] offset:-1920
	global_atomic_add v2, v3, s[14:15] offset:-1664
	global_atomic_add v2, v3, s[14:15] offset:-1408
	global_atomic_add v2, v3, s[14:15] offset:-1152
	global_atomic_add v2, v3, s[14:15] offset:-896
	global_atomic_add v2, v3, s[14:15] offset:-640
	global_atomic_add v2, v3, s[14:15] offset:-384
	global_atomic_add v2, v3, s[14:15] offset:-128
	buffer_inv sc1
	s_waitcnt vmcnt(0)
	s_branch .Lxb_dn_1

; DI void gbar(unsigned* ctr, unsigned& gen, unsigned G) {
;     asm volatile("s_waitcnt vmcnt(0)" ::: "memory");
;     __syncthreads();
;     gen += 1;
;     if (threadIdx.x == 0) {
;         __builtin_amdgcn_fence(__ATOMIC_RELEASE, "agent");
;         asm volatile("s_waitcnt vmcnt(0)" ::: "memory");
;         __hip_atomic_fetch_add(ctr, 1u, __ATOMIC_RELAXED, __HIP_MEMORY_SCOPE_AGENT);
;         while (__hip_atomic_load(ctr, __ATOMIC_RELAXED, __HIP_MEMORY_SCOPE_AGENT) < gen * G) __builtin_amdgcn_s_sleep(32);
;         __builtin_amdgcn_fence(__ATOMIC_ACQUIRE, "agent");
;         asm volatile("s_waitcnt vmcnt(0)" ::: "memory");
;     }
;     __syncthreads();
; }
.LBB0_1391:
	s_or_b64 exec, exec, s[72:73]
	v_cmp_gt_i32_e32 vcc, 4, v1
	v_cmp_lt_i32_e64 s[2:3], 4, v5
	s_and_b64 s[0:1], vcc, s[2:3]
	s_and_saveexec_b64 s[2:3], s[0:1]
	s_cbranch_execz .LBB0_1400
	s_waitcnt vmcnt(0)
	v_and_b32_e32 v2, 0x3ff, v0
	v_add_u32_e32 v210, 1, v210
	v_cmp_eq_u32_e32 vcc, 0, v2
	s_waitcnt vmcnt(0)
	s_barrier
	s_and_saveexec_b64 s[4:5], vcc
	s_cbranch_execz .LBB0_1399
	s_getreg_b32 s1, hwreg(HW_REG_XCC_ID, 0, 4)
	s_lshl_b32 s1, s1, 8
	s_add_u32 s12, s42, 0x600000
	s_addc_u32 s13, s43, 0
	s_add_u32 s12, s12, s1
	s_addc_u32 s13, s13, 0
	s_add_u32 s14, s42, 0x601000
	s_addc_u32 s15, s43, 0
	s_lshr_b32 s16, s86, 3
	v_mov_b32_e32 v2, 0
	v_mov_b32_e32 v3, 1
	v_mov_b32_e32 v7, v210
	global_atomic_add v4, v2, v3, s[12:13] sc0
	v_mul_lo_u32 v8, v7, s16
	s_mov_b32 s0, 0
	s_waitcnt vmcnt(0)
	v_add_u32_e32 v4, 1, v4
	v_cmp_eq_u32_e32 vcc, v4, v8
	s_cbranch_vccz .Lxb_nl_2
	buffer_wbl2 sc1
	s_waitcnt vmcnt(0)
	global_atomic_add v4, v2, v3, s[14:15] sc0
	v_lshlrev_b32_e32 v8, 3, v7
	s_waitcnt vmcnt(0)
	v_add_u32_e32 v4, 1, v4
	v_cmp_eq_u32_e32 vcc, v4, v8
	s_cbranch_vccz .Lxb_wt_2
	global_atomic_add v2, v3, s[14:15] offset:-3968
	global_atomic_add v2, v3, s[14:15] offset:-3712
	global_atomic_add v2, v3, s[14:15] offset:-3456
	global_atomic_add v2, v3, s[14:15] offset:-3200
	global_atomic_add v2, v3, s[14:15] offset:-2944
	global_atomic_add v2, v3, s[14:15] offset:-2688
	global_atomic_add v2, v3, s[14:15] offset:-2432
	global_atomic_add v2, v3, s[14:15] offset:-2176
	global_atomic_add v2, v3, s[14:15] offset:-1920
	global_atomic_add v2, v3, s[14:15] offset:-1664
	global_atomic_add v2, v3, s[14:15] offset:-1408
	global_atomic_add v2, v3, s[14:15] offset:-1152
	global_atomic_add v2, v3, s[14:15] offset:-896
	global_atomic_add v2, v3, s[14:15] offset:-640
	global_atomic_add v2, v3, s[14:15] offset:-384
	global_atomic_add v2, v3, s[14:15] offset:-128
	buffer_inv sc1
	s_waitcnt vmcnt(0)
	s_branch .Lxb_dn_2

; DI void gbar(unsigned* ctr, unsigned& gen, unsigned G) {
;     asm volatile("s_waitcnt vmcnt(0)" ::: "memory");
;     __syncthreads();
;     gen += 1;
;     if (threadIdx.x == 0) {
;         __builtin_amdgcn_fence(__ATOMIC_RELEASE, "agent");
;         asm volatile("s_waitcnt vmcnt(0)" ::: "memory");
;         __hip_atomic_fetch_add(ctr, 1u, __ATOMIC_RELAXED, __HIP_MEMORY_SCOPE_AGENT);
;         while (__hip_atomic_load(ctr, __ATOMIC_RELAXED, __HIP_MEMORY_SCOPE_AGENT) < gen * G) __builtin_amdgcn_s_sleep(32);
;         __builtin_amdgcn_fence(__ATOMIC_ACQUIRE, "agent");
;         asm volatile("s_waitcnt vmcnt(0)" ::: "memory");
;     }
;     __syncthreads();
; }
.LBB0_1445:
	s_or_b64 exec, exec, s[6:7]
	v_cmp_gt_i32_e32 vcc, 5, v1
	v_cmp_lt_i32_e64 s[2:3], 5, v5
	s_and_b64 s[0:1], vcc, s[2:3]
	s_and_saveexec_b64 s[2:3], s[0:1]
	s_cbranch_execz .LBB0_1454
	s_waitcnt vmcnt(0)
	v_and_b32_e32 v2, 0x3ff, v0
	v_add_u32_e32 v210, 1, v210
	v_cmp_eq_u32_e32 vcc, 0, v2
	s_waitcnt vmcnt(0) lgkmcnt(0)
	s_barrier
	s_and_saveexec_b64 s[4:5], vcc
	s_cbranch_execz .LBB0_1453
	s_getreg_b32 s1, hwreg(HW_REG_XCC_ID, 0, 4)
	s_lshl_b32 s1, s1, 8
	s_add_u32 s12, s42, 0x600000
	s_addc_u32 s13, s43, 0
	s_add_u32 s12, s12, s1
	s_addc_u32 s13, s13, 0
	s_add_u32 s14, s42, 0x601000
	s_addc_u32 s15, s43, 0
	s_lshr_b32 s16, s86, 3
	v_mov_b32_e32 v2, 0
	v_mov_b32_e32 v3, 1
	v_mov_b32_e32 v7, v210
	global_atomic_add v4, v2, v3, s[12:13] sc0
	v_mul_lo_u32 v8, v7, s16
	s_mov_b32 s0, 0
	s_waitcnt vmcnt(0)
	v_add_u32_e32 v4, 1, v4
	v_cmp_eq_u32_e32 vcc, v4, v8
	s_cbranch_vccz .Lxb_nl_3
	buffer_wbl2 sc1
	s_waitcnt vmcnt(0)
	global_atomic_add v4, v2, v3, s[14:15] sc0
	v_lshlrev_b32_e32 v8, 3, v7
	s_waitcnt vmcnt(0)
	v_add_u32_e32 v4, 1, v4
	v_cmp_eq_u32_e32 vcc, v4, v8
	s_cbranch_vccz .Lxb_wt_3
	global_atomic_add v2, v3, s[14:15] offset:-3968
	global_atomic_add v2, v3, s[14:15] offset:-3712
	global_atomic_add v2, v3, s[14:15] offset:-3456
	global_atomic_add v2, v3, s[14:15] offset:-3200
	global_atomic_add v2, v3, s[14:15] offset:-2944
	global_atomic_add v2, v3, s[14:15] offset:-2688
	global_atomic_add v2, v3, s[14:15] offset:-2432
	global_atomic_add v2, v3, s[14:15] offset:-2176
	global_atomic_add v2, v3, s[14:15] offset:-1920
	global_atomic_add v2, v3, s[14:15] offset:-1664
	global_atomic_add v2, v3, s[14:15] offset:-1408
	global_atomic_add v2, v3, s[14:15] offset:-1152
	global_atomic_add v2, v3, s[14:15] offset:-896
	global_atomic_add v2, v3, s[14:15] offset:-640
	global_atomic_add v2, v3, s[14:15] offset:-384
	global_atomic_add v2, v3, s[14:15] offset:-128
	buffer_inv sc1
	s_waitcnt vmcnt(0)
	s_branch .Lxb_dn_3

; DI void gbar(unsigned* ctr, unsigned& gen, unsigned G) {
;     asm volatile("s_waitcnt vmcnt(0)" ::: "memory");
;     __syncthreads();
;     gen += 1;
;     if (threadIdx.x == 0) {
;         __builtin_amdgcn_fence(__ATOMIC_RELEASE, "agent");
;         asm volatile("s_waitcnt vmcnt(0)" ::: "memory");
;         __hip_atomic_fetch_add(ctr, 1u, __ATOMIC_RELAXED, __HIP_MEMORY_SCOPE_AGENT);
;         while (__hip_atomic_load(ctr, __ATOMIC_RELAXED, __HIP_MEMORY_SCOPE_AGENT) < gen * G) __builtin_amdgcn_s_sleep(32);
;         __builtin_amdgcn_fence(__ATOMIC_ACQUIRE, "agent");
;         asm volatile("s_waitcnt vmcnt(0)" ::: "memory");
;     }
;     __syncthreads();
; }
.LBB0_1479:
	s_or_b64 exec, exec, s[4:5]
	v_cmp_gt_i32_e32 vcc, 6, v1
	v_cmp_lt_i32_e64 s[2:3], 6, v5
	s_and_b64 s[0:1], vcc, s[2:3]
	s_and_saveexec_b64 s[2:3], s[0:1]
	s_cbranch_execz .LBB0_1488
	s_waitcnt vmcnt(0)
	v_and_b32_e32 v2, 0x3ff, v0
	v_add_u32_e32 v210, 1, v210
	v_cmp_eq_u32_e32 vcc, 0, v2
	s_waitcnt vmcnt(0) lgkmcnt(0)
	s_barrier
	s_and_saveexec_b64 s[4:5], vcc
	s_cbranch_execz .LBB0_1487
	s_getreg_b32 s1, hwreg(HW_REG_XCC_ID, 0, 4)
	s_lshl_b32 s1, s1, 8
	s_add_u32 s12, s42, 0x600000
	s_addc_u32 s13, s43, 0
	s_add_u32 s12, s12, s1
	s_addc_u32 s13, s13, 0
	s_add_u32 s14, s42, 0x601000
	s_addc_u32 s15, s43, 0
	s_lshr_b32 s16, s86, 3
	v_mov_b32_e32 v2, 0
	v_mov_b32_e32 v3, 1
	v_mov_b32_e32 v7, v210
	global_atomic_add v4, v2, v3, s[12:13] sc0
	v_mul_lo_u32 v8, v7, s16
	s_mov_b32 s0, 0
	s_waitcnt vmcnt(0)
	v_add_u32_e32 v4, 1, v4
	v_cmp_eq_u32_e32 vcc, v4, v8
	s_cbranch_vccz .Lxb_nl_4
	buffer_wbl2 sc1
	s_waitcnt vmcnt(0)
	global_atomic_add v4, v2, v3, s[14:15] sc0
	v_lshlrev_b32_e32 v8, 3, v7
	s_waitcnt vmcnt(0)
	v_add_u32_e32 v4, 1, v4
	v_cmp_eq_u32_e32 vcc, v4, v8
	s_cbranch_vccz .Lxb_wt_4
	global_atomic_add v2, v3, s[14:15] offset:-3968
	global_atomic_add v2, v3, s[14:15] offset:-3712
	global_atomic_add v2, v3, s[14:15] offset:-3456
	global_atomic_add v2, v3, s[14:15] offset:-3200
	global_atomic_add v2, v3, s[14:15] offset:-2944
	global_atomic_add v2, v3, s[14:15] offset:-2688
	global_atomic_add v2, v3, s[14:15] offset:-2432
	global_atomic_add v2, v3, s[14:15] offset:-2176
	global_atomic_add v2, v3, s[14:15] offset:-1920
	global_atomic_add v2, v3, s[14:15] offset:-1664
	global_atomic_add v2, v3, s[14:15] offset:-1408
	global_atomic_add v2, v3, s[14:15] offset:-1152
	global_atomic_add v2, v3, s[14:15] offset:-896
	global_atomic_add v2, v3, s[14:15] offset:-640
	global_atomic_add v2, v3, s[14:15] offset:-384
	global_atomic_add v2, v3, s[14:15] offset:-128
	buffer_inv sc1
	s_waitcnt vmcnt(0)
	s_branch .Lxb_dn_4

; DI void gbar(unsigned* ctr, unsigned& gen, unsigned G) {
;     asm volatile("s_waitcnt vmcnt(0)" ::: "memory");
;     __syncthreads();
;     gen += 1;
;     if (threadIdx.x == 0) {
;         __builtin_amdgcn_fence(__ATOMIC_RELEASE, "agent");
;         asm volatile("s_waitcnt vmcnt(0)" ::: "memory");
;         __hip_atomic_fetch_add(ctr, 1u, __ATOMIC_RELAXED, __HIP_MEMORY_SCOPE_AGENT);
;         while (__hip_atomic_load(ctr, __ATOMIC_RELAXED, __HIP_MEMORY_SCOPE_AGENT) < gen * G) __builtin_amdgcn_s_sleep(32);
;         __builtin_amdgcn_fence(__ATOMIC_ACQUIRE, "agent");
;         asm volatile("s_waitcnt vmcnt(0)" ::: "memory");
;     }
;     __syncthreads();
; }
.LBB0_1531:
	s_or_b64 exec, exec, s[6:7]
	v_cmp_gt_i32_e32 vcc, 7, v1
	v_cmp_lt_i32_e64 s[2:3], 7, v5
	s_and_b64 s[0:1], vcc, s[2:3]
	s_and_saveexec_b64 s[2:3], s[0:1]
	s_cbranch_execz .LBB0_1540
	s_waitcnt vmcnt(0)
	v_and_b32_e32 v2, 0x3ff, v0
	v_add_u32_e32 v210, 1, v210
	v_cmp_eq_u32_e32 vcc, 0, v2
	s_waitcnt vmcnt(0) lgkmcnt(0)
	s_barrier
	s_and_saveexec_b64 s[4:5], vcc
	s_cbranch_execz .LBB0_1539
	s_getreg_b32 s1, hwreg(HW_REG_XCC_ID, 0, 4)
	s_lshl_b32 s1, s1, 8
	s_add_u32 s12, s42, 0x600000
	s_addc_u32 s13, s43, 0
	s_add_u32 s12, s12, s1
	s_addc_u32 s13, s13, 0
	s_add_u32 s14, s42, 0x601000
	s_addc_u32 s15, s43, 0
	s_lshr_b32 s16, s86, 3
	v_mov_b32_e32 v2, 0
	v_mov_b32_e32 v3, 1
	v_mov_b32_e32 v7, v210
	global_atomic_add v4, v2, v3, s[12:13] sc0
	v_mul_lo_u32 v8, v7, s16
	s_mov_b32 s0, 0
	s_waitcnt vmcnt(0)
	v_add_u32_e32 v4, 1, v4
	v_cmp_eq_u32_e32 vcc, v4, v8
	s_cbranch_vccz .Lxb_nl_5
	buffer_wbl2 sc1
	s_waitcnt vmcnt(0)
	global_atomic_add v4, v2, v3, s[14:15] sc0
	v_lshlrev_b32_e32 v8, 3, v7
	s_waitcnt vmcnt(0)
	v_add_u32_e32 v4, 1, v4
	v_cmp_eq_u32_e32 vcc, v4, v8
	s_cbranch_vccz .Lxb_wt_5
	global_atomic_add v2, v3, s[14:15] offset:-3968
	global_atomic_add v2, v3, s[14:15] offset:-3712
	global_atomic_add v2, v3, s[14:15] offset:-3456
	global_atomic_add v2, v3, s[14:15] offset:-3200
	global_atomic_add v2, v3, s[14:15] offset:-2944
	global_atomic_add v2, v3, s[14:15] offset:-2688
	global_atomic_add v2, v3, s[14:15] offset:-2432
	global_atomic_add v2, v3, s[14:15] offset:-2176
	global_atomic_add v2, v3, s[14:15] offset:-1920
	global_atomic_add v2, v3, s[14:15] offset:-1664
	global_atomic_add v2, v3, s[14:15] offset:-1408
	global_atomic_add v2, v3, s[14:15] offset:-1152
	global_atomic_add v2, v3, s[14:15] offset:-896
	global_atomic_add v2, v3, s[14:15] offset:-640
	global_atomic_add v2, v3, s[14:15] offset:-384
	global_atomic_add v2, v3, s[14:15] offset:-128
	buffer_inv sc1
	s_waitcnt vmcnt(0)
	s_branch .Lxb_dn_5

; DI void gbar(unsigned* ctr, unsigned& gen, unsigned G) {
;     asm volatile("s_waitcnt vmcnt(0)" ::: "memory");
;     __syncthreads();
;     gen += 1;
;     if (threadIdx.x == 0) {
;         __builtin_amdgcn_fence(__ATOMIC_RELEASE, "agent");
;         asm volatile("s_waitcnt vmcnt(0)" ::: "memory");
;         __hip_atomic_fetch_add(ctr, 1u, __ATOMIC_RELAXED, __HIP_MEMORY_SCOPE_AGENT);
;         while (__hip_atomic_load(ctr, __ATOMIC_RELAXED, __HIP_MEMORY_SCOPE_AGENT) < gen * G) __builtin_amdgcn_s_sleep(32);
;         __builtin_amdgcn_fence(__ATOMIC_ACQUIRE, "agent");
;         asm volatile("s_waitcnt vmcnt(0)" ::: "memory");
;     }
;     __syncthreads();
; }
.LBB0_2532:
	s_or_b64 exec, exec, s[12:13]
	v_cmp_gt_i32_e32 vcc, 8, v1
	v_cmp_lt_i32_e64 s[2:3], 8, v5
	s_and_b64 s[0:1], vcc, s[2:3]
	s_and_saveexec_b64 s[2:3], s[0:1]
	s_cbranch_execz .LBB0_2541
	s_waitcnt vmcnt(0)
	v_and_b32_e32 v2, 0x3ff, v0
	v_add_u32_e32 v210, 1, v210
	v_cmp_eq_u32_e32 vcc, 0, v2
	s_waitcnt vmcnt(0) lgkmcnt(0)
	s_barrier
	s_and_saveexec_b64 s[4:5], vcc
	s_cbranch_execz .LBB0_2540
	s_getreg_b32 s1, hwreg(HW_REG_XCC_ID, 0, 4)
	s_lshl_b32 s1, s1, 8
	s_add_u32 s12, s42, 0x600000
	s_addc_u32 s13, s43, 0
	s_add_u32 s12, s12, s1
	s_addc_u32 s13, s13, 0
	s_add_u32 s14, s42, 0x601000
	s_addc_u32 s15, s43, 0
	s_lshr_b32 s16, s86, 3
	v_mov_b32_e32 v2, 0
	v_mov_b32_e32 v3, 1
	v_mov_b32_e32 v7, v210
	global_atomic_add v4, v2, v3, s[12:13] sc0
	v_mul_lo_u32 v8, v7, s16
	s_mov_b32 s0, 0
	s_waitcnt vmcnt(0)
	v_add_u32_e32 v4, 1, v4
	v_cmp_eq_u32_e32 vcc, v4, v8
	s_cbranch_vccz .Lxb_nl_6
	buffer_wbl2 sc1
	s_waitcnt vmcnt(0)
	global_atomic_add v4, v2, v3, s[14:15] sc0
	v_lshlrev_b32_e32 v8, 3, v7
	s_waitcnt vmcnt(0)
	v_add_u32_e32 v4, 1, v4
	v_cmp_eq_u32_e32 vcc, v4, v8
	s_cbranch_vccz .Lxb_wt_6
	global_atomic_add v2, v3, s[14:15] offset:-3968
	global_atomic_add v2, v3, s[14:15] offset:-3712
	global_atomic_add v2, v3, s[14:15] offset:-3456
	global_atomic_add v2, v3, s[14:15] offset:-3200
	global_atomic_add v2, v3, s[14:15] offset:-2944
	global_atomic_add v2, v3, s[14:15] offset:-2688
	global_atomic_add v2, v3, s[14:15] offset:-2432
	global_atomic_add v2, v3, s[14:15] offset:-2176
	global_atomic_add v2, v3, s[14:15] offset:-1920
	global_atomic_add v2, v3, s[14:15] offset:-1664
	global_atomic_add v2, v3, s[14:15] offset:-1408
	global_atomic_add v2, v3, s[14:15] offset:-1152
	global_atomic_add v2, v3, s[14:15] offset:-896
	global_atomic_add v2, v3, s[14:15] offset:-640
	global_atomic_add v2, v3, s[14:15] offset:-384
	global_atomic_add v2, v3, s[14:15] offset:-128
	buffer_inv sc1
	s_waitcnt vmcnt(0)
	s_branch .Lxb_dn_6

; DI void gbar(unsigned* ctr, unsigned& gen, unsigned G) {
;     asm volatile("s_waitcnt vmcnt(0)" ::: "memory");
;     __syncthreads();
;     gen += 1;
;     if (threadIdx.x == 0) {
;         __builtin_amdgcn_fence(__ATOMIC_RELEASE, "agent");
;         asm volatile("s_waitcnt vmcnt(0)" ::: "memory");
;         __hip_atomic_fetch_add(ctr, 1u, __ATOMIC_RELAXED, __HIP_MEMORY_SCOPE_AGENT);
;         while (__hip_atomic_load(ctr, __ATOMIC_RELAXED, __HIP_MEMORY_SCOPE_AGENT) < gen * G) __builtin_amdgcn_s_sleep(32);
;         __builtin_amdgcn_fence(__ATOMIC_ACQUIRE, "agent");
;         asm volatile("s_waitcnt vmcnt(0)" ::: "memory");
;     }
;     __syncthreads();
; }
.LBB0_2545:
	s_or_b64 exec, exec, s[8:9]
	v_cmp_lt_i32_e64 s[2:3], 9, v5
	s_and_b64 s[0:1], vcc, s[2:3]
	s_and_saveexec_b64 s[2:3], s[0:1]
	s_cbranch_execz .LBB0_2554
	s_waitcnt vmcnt(0)
	v_and_b32_e32 v2, 0x3ff, v0
	v_add_u32_e32 v210, 1, v210
	v_cmp_eq_u32_e32 vcc, 0, v2
	s_waitcnt vmcnt(0)
	s_barrier
	s_and_saveexec_b64 s[4:5], vcc
	s_cbranch_execz .LBB0_2553
	s_getreg_b32 s1, hwreg(HW_REG_XCC_ID, 0, 4)
	s_lshl_b32 s1, s1, 8
	s_add_u32 s12, s42, 0x600000
	s_addc_u32 s13, s43, 0
	s_add_u32 s12, s12, s1
	s_addc_u32 s13, s13, 0
	s_add_u32 s14, s42, 0x601000
	s_addc_u32 s15, s43, 0
	s_lshr_b32 s16, s86, 3
	v_mov_b32_e32 v2, 0
	v_mov_b32_e32 v3, 1
	v_mov_b32_e32 v7, v210
	global_atomic_add v4, v2, v3, s[12:13] sc0
	v_mul_lo_u32 v8, v7, s16
	s_mov_b32 s0, 0
	s_waitcnt vmcnt(0)
	v_add_u32_e32 v4, 1, v4
	v_cmp_eq_u32_e32 vcc, v4, v8
	s_cbranch_vccz .Lxb_nl_7
	buffer_wbl2 sc1
	s_waitcnt vmcnt(0)
	global_atomic_add v4, v2, v3, s[14:15] sc0
	v_lshlrev_b32_e32 v8, 3, v7
	s_waitcnt vmcnt(0)
	v_add_u32_e32 v4, 1, v4
	v_cmp_eq_u32_e32 vcc, v4, v8
	s_cbranch_vccz .Lxb_wt_7
	global_atomic_add v2, v3, s[14:15] offset:-3968
	global_atomic_add v2, v3, s[14:15] offset:-3712
	global_atomic_add v2, v3, s[14:15] offset:-3456
	global_atomic_add v2, v3, s[14:15] offset:-3200
	global_atomic_add v2, v3, s[14:15] offset:-2944
	global_atomic_add v2, v3, s[14:15] offset:-2688
	global_atomic_add v2, v3, s[14:15] offset:-2432
	global_atomic_add v2, v3, s[14:15] offset:-2176
	global_atomic_add v2, v3, s[14:15] offset:-1920
	global_atomic_add v2, v3, s[14:15] offset:-1664
	global_atomic_add v2, v3, s[14:15] offset:-1408
	global_atomic_add v2, v3, s[14:15] offset:-1152
	global_atomic_add v2, v3, s[14:15] offset:-896
	global_atomic_add v2, v3, s[14:15] offset:-640
	global_atomic_add v2, v3, s[14:15] offset:-384
	global_atomic_add v2, v3, s[14:15] offset:-128
	buffer_inv sc1
	s_waitcnt vmcnt(0)
	s_branch .Lxb_dn_7

; DI void gbar(unsigned* ctr, unsigned& gen, unsigned G) {
;     asm volatile("s_waitcnt vmcnt(0)" ::: "memory");
;     __syncthreads();
;     gen += 1;
;     if (threadIdx.x == 0) {
;         __builtin_amdgcn_fence(__ATOMIC_RELEASE, "agent");
;         asm volatile("s_waitcnt vmcnt(0)" ::: "memory");
;         __hip_atomic_fetch_add(ctr, 1u, __ATOMIC_RELAXED, __HIP_MEMORY_SCOPE_AGENT);
;         while (__hip_atomic_load(ctr, __ATOMIC_RELAXED, __HIP_MEMORY_SCOPE_AGENT) < gen * G) __builtin_amdgcn_s_sleep(32);
;         __builtin_amdgcn_fence(__ATOMIC_ACQUIRE, "agent");
;         asm volatile("s_waitcnt vmcnt(0)" ::: "memory");
;     }
;     __syncthreads();
; }
.LBB0_3580:
	s_or_b64 exec, exec, s[2:3]
	v_cmp_gt_i32_e32 vcc, 10, v1
	v_cmp_lt_i32_e64 s[2:3], 10, v5
	s_and_b64 s[0:1], vcc, s[2:3]
	s_and_saveexec_b64 s[2:3], s[0:1]
	s_cbranch_execz .LBB0_3589
	s_waitcnt vmcnt(0)
	v_and_b32_e32 v2, 0x3ff, v0
	v_add_u32_e32 v210, 1, v210
	v_cmp_eq_u32_e32 vcc, 0, v2
	s_waitcnt vmcnt(0)
	s_barrier
	s_and_saveexec_b64 s[4:5], vcc
	s_cbranch_execz .LBB0_3588
	s_getreg_b32 s1, hwreg(HW_REG_XCC_ID, 0, 4)
	s_lshl_b32 s1, s1, 8
	s_add_u32 s12, s42, 0x600000
	s_addc_u32 s13, s43, 0
	s_add_u32 s12, s12, s1
	s_addc_u32 s13, s13, 0
	s_add_u32 s14, s42, 0x601000
	s_addc_u32 s15, s43, 0
	s_lshr_b32 s16, s86, 3
	v_mov_b32_e32 v2, 0
	v_mov_b32_e32 v3, 1
	v_mov_b32_e32 v7, v210
	global_atomic_add v4, v2, v3, s[12:13] sc0
	v_mul_lo_u32 v8, v7, s16
	s_mov_b32 s0, 0
	s_waitcnt vmcnt(0)
	v_add_u32_e32 v4, 1, v4
	v_cmp_eq_u32_e32 vcc, v4, v8
	s_cbranch_vccz .Lxb_nl_8
	buffer_wbl2 sc1
	s_waitcnt vmcnt(0)
	global_atomic_add v4, v2, v3, s[14:15] sc0
	v_lshlrev_b32_e32 v8, 3, v7
	s_waitcnt vmcnt(0)
	v_add_u32_e32 v4, 1, v4
	v_cmp_eq_u32_e32 vcc, v4, v8
	s_cbranch_vccz .Lxb_wt_8
	global_atomic_add v2, v3, s[14:15] offset:-3968
	global_atomic_add v2, v3, s[14:15] offset:-3712
	global_atomic_add v2, v3, s[14:15] offset:-3456
	global_atomic_add v2, v3, s[14:15] offset:-3200
	global_atomic_add v2, v3, s[14:15] offset:-2944
	global_atomic_add v2, v3, s[14:15] offset:-2688
	global_atomic_add v2, v3, s[14:15] offset:-2432
	global_atomic_add v2, v3, s[14:15] offset:-2176
	global_atomic_add v2, v3, s[14:15] offset:-1920
	global_atomic_add v2, v3, s[14:15] offset:-1664
	global_atomic_add v2, v3, s[14:15] offset:-1408
	global_atomic_add v2, v3, s[14:15] offset:-1152
	global_atomic_add v2, v3, s[14:15] offset:-896
	global_atomic_add v2, v3, s[14:15] offset:-640
	global_atomic_add v2, v3, s[14:15] offset:-384
	global_atomic_add v2, v3, s[14:15] offset:-128
	buffer_inv sc1
	s_waitcnt vmcnt(0)
	s_branch .Lxb_dn_8

; DI void gbar(unsigned* ctr, unsigned& gen, unsigned G) {
;     asm volatile("s_waitcnt vmcnt(0)" ::: "memory");
;     __syncthreads();
;     gen += 1;
;     if (threadIdx.x == 0) {
;         __builtin_amdgcn_fence(__ATOMIC_RELEASE, "agent");
;         asm volatile("s_waitcnt vmcnt(0)" ::: "memory");
;         __hip_atomic_fetch_add(ctr, 1u, __ATOMIC_RELAXED, __HIP_MEMORY_SCOPE_AGENT);
;         while (__hip_atomic_load(ctr, __ATOMIC_RELAXED, __HIP_MEMORY_SCOPE_AGENT) < gen * G) __builtin_amdgcn_s_sleep(32);
;         __builtin_amdgcn_fence(__ATOMIC_ACQUIRE, "agent");
;         asm volatile("s_waitcnt vmcnt(0)" ::: "memory");
;     }
;     __syncthreads();
; }
.LBB0_3644:
	s_or_b64 exec, exec, s[8:9]
	v_cmp_gt_i32_e32 vcc, 11, v1
	v_cmp_lt_i32_e64 s[2:3], 11, v5
	s_and_b64 s[0:1], vcc, s[2:3]
	s_and_saveexec_b64 s[2:3], s[0:1]
	s_cbranch_execz .LBB0_3653
	s_waitcnt vmcnt(0)
	v_and_b32_e32 v2, 0x3ff, v0
	v_add_u32_e32 v210, 1, v210
	v_cmp_eq_u32_e32 vcc, 0, v2
	s_waitcnt vmcnt(0)
	s_barrier
	s_and_saveexec_b64 s[4:5], vcc
	s_cbranch_execz .LBB0_3652
	s_getreg_b32 s1, hwreg(HW_REG_XCC_ID, 0, 4)
	s_lshl_b32 s1, s1, 8
	s_add_u32 s12, s42, 0x600000
	s_addc_u32 s13, s43, 0
	s_add_u32 s12, s12, s1
	s_addc_u32 s13, s13, 0
	s_add_u32 s14, s42, 0x601000
	s_addc_u32 s15, s43, 0
	s_lshr_b32 s16, s86, 3
	v_mov_b32_e32 v2, 0
	v_mov_b32_e32 v3, 1
	v_mov_b32_e32 v7, v210
	global_atomic_add v4, v2, v3, s[12:13] sc0
	v_mul_lo_u32 v8, v7, s16
	s_mov_b32 s0, 0
	s_waitcnt vmcnt(0)
	v_add_u32_e32 v4, 1, v4
	v_cmp_eq_u32_e32 vcc, v4, v8
	s_cbranch_vccz .Lxb_nl_9
	buffer_wbl2 sc1
	s_waitcnt vmcnt(0)
	global_atomic_add v4, v2, v3, s[14:15] sc0
	v_lshlrev_b32_e32 v8, 3, v7
	s_waitcnt vmcnt(0)
	v_add_u32_e32 v4, 1, v4
	v_cmp_eq_u32_e32 vcc, v4, v8
	s_cbranch_vccz .Lxb_wt_9
	global_atomic_add v2, v3, s[14:15] offset:-3968
	global_atomic_add v2, v3, s[14:15] offset:-3712
	global_atomic_add v2, v3, s[14:15] offset:-3456
	global_atomic_add v2, v3, s[14:15] offset:-3200
	global_atomic_add v2, v3, s[14:15] offset:-2944
	global_atomic_add v2, v3, s[14:15] offset:-2688
	global_atomic_add v2, v3, s[14:15] offset:-2432
	global_atomic_add v2, v3, s[14:15] offset:-2176
	global_atomic_add v2, v3, s[14:15] offset:-1920
	global_atomic_add v2, v3, s[14:15] offset:-1664
	global_atomic_add v2, v3, s[14:15] offset:-1408
	global_atomic_add v2, v3, s[14:15] offset:-1152
	global_atomic_add v2, v3, s[14:15] offset:-896
	global_atomic_add v2, v3, s[14:15] offset:-640
	global_atomic_add v2, v3, s[14:15] offset:-384
	global_atomic_add v2, v3, s[14:15] offset:-128
	buffer_inv sc1
	s_waitcnt vmcnt(0)
	s_branch .Lxb_dn_9

; DI void gbar(unsigned* ctr, unsigned& gen, unsigned G) {
;     asm volatile("s_waitcnt vmcnt(0)" ::: "memory");
;     __syncthreads();
;     gen += 1;
;     if (threadIdx.x == 0) {
;         __builtin_amdgcn_fence(__ATOMIC_RELEASE, "agent");
;         asm volatile("s_waitcnt vmcnt(0)" ::: "memory");
;         __hip_atomic_fetch_add(ctr, 1u, __ATOMIC_RELAXED, __HIP_MEMORY_SCOPE_AGENT);
;         while (__hip_atomic_load(ctr, __ATOMIC_RELAXED, __HIP_MEMORY_SCOPE_AGENT) < gen * G) __builtin_amdgcn_s_sleep(32);
;         __builtin_amdgcn_fence(__ATOMIC_ACQUIRE, "agent");
;         asm volatile("s_waitcnt vmcnt(0)" ::: "memory");
;     }
;     __syncthreads();
; }
.LBB0_3696:
	s_or_b64 exec, exec, s[6:7]
	v_cmp_gt_i32_e32 vcc, 12, v1
	v_cmp_lt_i32_e64 s[2:3], 12, v5
	s_and_b64 s[0:1], vcc, s[2:3]
	s_and_saveexec_b64 s[2:3], s[0:1]
	s_cbranch_execz .LBB0_3705
	s_waitcnt vmcnt(0)
	v_and_b32_e32 v2, 0x3ff, v0
	v_add_u32_e32 v210, 1, v210
	v_cmp_eq_u32_e32 vcc, 0, v2
	s_waitcnt vmcnt(0) lgkmcnt(0)
	s_barrier
	s_and_saveexec_b64 s[4:5], vcc
	s_cbranch_execz .LBB0_3704
	s_getreg_b32 s1, hwreg(HW_REG_XCC_ID, 0, 4)
	s_lshl_b32 s1, s1, 8
	s_add_u32 s12, s42, 0x600000
	s_addc_u32 s13, s43, 0
	s_add_u32 s12, s12, s1
	s_addc_u32 s13, s13, 0
	s_add_u32 s14, s42, 0x601000
	s_addc_u32 s15, s43, 0
	s_lshr_b32 s16, s86, 3
	v_mov_b32_e32 v2, 0
	v_mov_b32_e32 v3, 1
	v_mov_b32_e32 v7, v210
	global_atomic_add v4, v2, v3, s[12:13] sc0
	v_mul_lo_u32 v8, v7, s16
	s_mov_b32 s0, 0
	s_waitcnt vmcnt(0)
	v_add_u32_e32 v4, 1, v4
	v_cmp_eq_u32_e32 vcc, v4, v8
	s_cbranch_vccz .Lxb_nl_10
	buffer_wbl2 sc1
	s_waitcnt vmcnt(0)
	global_atomic_add v4, v2, v3, s[14:15] sc0
	v_lshlrev_b32_e32 v8, 3, v7
	s_waitcnt vmcnt(0)
	v_add_u32_e32 v4, 1, v4
	v_cmp_eq_u32_e32 vcc, v4, v8
	s_cbranch_vccz .Lxb_wt_10
	global_atomic_add v2, v3, s[14:15] offset:-3968
	global_atomic_add v2, v3, s[14:15] offset:-3712
	global_atomic_add v2, v3, s[14:15] offset:-3456
	global_atomic_add v2, v3, s[14:15] offset:-3200
	global_atomic_add v2, v3, s[14:15] offset:-2944
	global_atomic_add v2, v3, s[14:15] offset:-2688
	global_atomic_add v2, v3, s[14:15] offset:-2432
	global_atomic_add v2, v3, s[14:15] offset:-2176
	global_atomic_add v2, v3, s[14:15] offset:-1920
	global_atomic_add v2, v3, s[14:15] offset:-1664
	global_atomic_add v2, v3, s[14:15] offset:-1408
	global_atomic_add v2, v3, s[14:15] offset:-1152
	global_atomic_add v2, v3, s[14:15] offset:-896
	global_atomic_add v2, v3, s[14:15] offset:-640
	global_atomic_add v2, v3, s[14:15] offset:-384
	global_atomic_add v2, v3, s[14:15] offset:-128
	buffer_inv sc1
	s_waitcnt vmcnt(0)
	s_branch .Lxb_dn_10

; DI void gbar(unsigned* ctr, unsigned& gen, unsigned G) {
;     asm volatile("s_waitcnt vmcnt(0)" ::: "memory");
;     __syncthreads();
;     gen += 1;
;     if (threadIdx.x == 0) {
;         __builtin_amdgcn_fence(__ATOMIC_RELEASE, "agent");
;         asm volatile("s_waitcnt vmcnt(0)" ::: "memory");
;         __hip_atomic_fetch_add(ctr, 1u, __ATOMIC_RELAXED, __HIP_MEMORY_SCOPE_AGENT);
;         while (__hip_atomic_load(ctr, __ATOMIC_RELAXED, __HIP_MEMORY_SCOPE_AGENT) < gen * G) __builtin_amdgcn_s_sleep(32);
;         __builtin_amdgcn_fence(__ATOMIC_ACQUIRE, "agent");
;         asm volatile("s_waitcnt vmcnt(0)" ::: "memory");
;     }
;     __syncthreads();
; }
.LBB0_3730:
	s_or_b64 exec, exec, s[4:5]
	v_cmp_gt_i32_e32 vcc, 13, v1
	v_cmp_lt_i32_e64 s[2:3], 13, v5
	s_and_b64 s[0:1], vcc, s[2:3]
	s_and_saveexec_b64 s[2:3], s[0:1]
	s_cbranch_execz .LBB0_3739
	s_waitcnt vmcnt(0)
	v_and_b32_e32 v2, 0x3ff, v0
	v_add_u32_e32 v210, 1, v210
	v_cmp_eq_u32_e32 vcc, 0, v2
	s_waitcnt vmcnt(0) lgkmcnt(0)
	s_barrier
	s_and_saveexec_b64 s[4:5], vcc
	s_cbranch_execz .LBB0_3738
	s_getreg_b32 s1, hwreg(HW_REG_XCC_ID, 0, 4)
	s_lshl_b32 s1, s1, 8
	s_add_u32 s12, s42, 0x600000
	s_addc_u32 s13, s43, 0
	s_add_u32 s12, s12, s1
	s_addc_u32 s13, s13, 0
	s_add_u32 s14, s42, 0x601000
	s_addc_u32 s15, s43, 0
	s_lshr_b32 s16, s86, 3
	v_mov_b32_e32 v2, 0
	v_mov_b32_e32 v3, 1
	v_mov_b32_e32 v7, v210
	global_atomic_add v4, v2, v3, s[12:13] sc0
	v_mul_lo_u32 v8, v7, s16
	s_mov_b32 s0, 0
	s_waitcnt vmcnt(0)
	v_add_u32_e32 v4, 1, v4
	v_cmp_eq_u32_e32 vcc, v4, v8
	s_cbranch_vccz .Lxb_nl_11
	buffer_wbl2 sc1
	s_waitcnt vmcnt(0)
	global_atomic_add v4, v2, v3, s[14:15] sc0
	v_lshlrev_b32_e32 v8, 3, v7
	s_waitcnt vmcnt(0)
	v_add_u32_e32 v4, 1, v4
	v_cmp_eq_u32_e32 vcc, v4, v8
	s_cbranch_vccz .Lxb_wt_11
	global_atomic_add v2, v3, s[14:15] offset:-3968
	global_atomic_add v2, v3, s[14:15] offset:-3712
	global_atomic_add v2, v3, s[14:15] offset:-3456
	global_atomic_add v2, v3, s[14:15] offset:-3200
	global_atomic_add v2, v3, s[14:15] offset:-2944
	global_atomic_add v2, v3, s[14:15] offset:-2688
	global_atomic_add v2, v3, s[14:15] offset:-2432
	global_atomic_add v2, v3, s[14:15] offset:-2176
	global_atomic_add v2, v3, s[14:15] offset:-1920
	global_atomic_add v2, v3, s[14:15] offset:-1664
	global_atomic_add v2, v3, s[14:15] offset:-1408
	global_atomic_add v2, v3, s[14:15] offset:-1152
	global_atomic_add v2, v3, s[14:15] offset:-896
	global_atomic_add v2, v3, s[14:15] offset:-640
	global_atomic_add v2, v3, s[14:15] offset:-384
	global_atomic_add v2, v3, s[14:15] offset:-128
	buffer_inv sc1
	s_waitcnt vmcnt(0)
	s_branch .Lxb_dn_11

; DI void gbar(unsigned* ctr, unsigned& gen, unsigned G) {
;     asm volatile("s_waitcnt vmcnt(0)" ::: "memory");
;     __syncthreads();
;     gen += 1;
;     if (threadIdx.x == 0) {
;         __builtin_amdgcn_fence(__ATOMIC_RELEASE, "agent");
;         asm volatile("s_waitcnt vmcnt(0)" ::: "memory");
;         __hip_atomic_fetch_add(ctr, 1u, __ATOMIC_RELAXED, __HIP_MEMORY_SCOPE_AGENT);
;         while (__hip_atomic_load(ctr, __ATOMIC_RELAXED, __HIP_MEMORY_SCOPE_AGENT) < gen * G) __builtin_amdgcn_s_sleep(32);
;         __builtin_amdgcn_fence(__ATOMIC_ACQUIRE, "agent");
;         asm volatile("s_waitcnt vmcnt(0)" ::: "memory");
;     }
;     __syncthreads();
; }
.LBB0_3782:
	s_or_b64 exec, exec, s[6:7]
	v_cmp_gt_i32_e32 vcc, 14, v1
	v_cmp_lt_i32_e64 s[2:3], 14, v5
	s_and_b64 s[0:1], vcc, s[2:3]
	s_and_saveexec_b64 s[2:3], s[0:1]
	s_cbranch_execz .LBB0_3791
	s_waitcnt vmcnt(0)
	v_and_b32_e32 v2, 0x3ff, v0
	v_cmp_eq_u32_e32 vcc, 0, v2
	s_waitcnt vmcnt(0) lgkmcnt(0)
	s_barrier
	s_and_saveexec_b64 s[4:5], vcc
	s_cbranch_execz .LBB0_3790
	s_getreg_b32 s1, hwreg(HW_REG_XCC_ID, 0, 4)
	s_lshl_b32 s1, s1, 8
	s_add_u32 s12, s42, 0x600000
	s_addc_u32 s13, s43, 0
	s_add_u32 s12, s12, s1
	s_addc_u32 s13, s13, 0
	s_add_u32 s14, s42, 0x601000
	s_addc_u32 s15, s43, 0
	s_lshr_b32 s16, s86, 3
	v_mov_b32_e32 v2, 0
	v_mov_b32_e32 v3, 1
	v_add_u32_e32 v7, 1, v210
	global_atomic_add v4, v2, v3, s[12:13] sc0
	v_mul_lo_u32 v8, v7, s16
	s_mov_b32 s0, 0
	s_waitcnt vmcnt(0)
	v_add_u32_e32 v4, 1, v4
	v_cmp_eq_u32_e32 vcc, v4, v8
	s_cbranch_vccz .Lxb_nl_12
	buffer_wbl2 sc1
	s_waitcnt vmcnt(0)
	global_atomic_add v4, v2, v3, s[14:15] sc0
	v_lshlrev_b32_e32 v8, 3, v7
	s_waitcnt vmcnt(0)
	v_add_u32_e32 v4, 1, v4
	v_cmp_eq_u32_e32 vcc, v4, v8
	s_cbranch_vccz .Lxb_wt_12
	global_atomic_add v2, v3, s[14:15] offset:-3968
	global_atomic_add v2, v3, s[14:15] offset:-3712
	global_atomic_add v2, v3, s[14:15] offset:-3456
	global_atomic_add v2, v3, s[14:15] offset:-3200
	global_atomic_add v2, v3, s[14:15] offset:-2944
	global_atomic_add v2, v3, s[14:15] offset:-2688
	global_atomic_add v2, v3, s[14:15] offset:-2432
	global_atomic_add v2, v3, s[14:15] offset:-2176
	global_atomic_add v2, v3, s[14:15] offset:-1920
	global_atomic_add v2, v3, s[14:15] offset:-1664
	global_atomic_add v2, v3, s[14:15] offset:-1408
	global_atomic_add v2, v3, s[14:15] offset:-1152
	global_atomic_add v2, v3, s[14:15] offset:-896
	global_atomic_add v2, v3, s[14:15] offset:-640
	global_atomic_add v2, v3, s[14:15] offset:-384
	global_atomic_add v2, v3, s[14:15] offset:-128
	buffer_inv sc1
	s_waitcnt vmcnt(0)
	s_branch .Lxb_dn_12
